# P7 full-unit epilogue: lanes remapped with DPP row_ror so each 16-byte load/store instruction covers 8 full 128-byte row segments (on top of v20)
# baseline (speedup 1.0000x reference)
;     __device__ __forceinline__ void operator()(const f32x4 (&acc)[2][2][4][2], const pg8::Unit& u, int wr, int wc, int fr, int fq) const {
;         const int row0 = u.pm * 256 + wr * 64 + fr; const int colb = u.pn * 256 + 32 * wc + 8 * fq;
;         if (u.nt == 0) {
; #pragma unroll
;             for (int ai = 0; ai < 2; ++ai) {
;                 f32x4 xv[4][2][2];
; #pragma unroll
;                 for (int m = 0; m < 4; ++m)
; #pragma unroll
;                     for (int bj = 0; bj < 2; ++bj) { const float* xr = out + (size_t)(row0 + ai * 128 + m * 16) * DM + colb + 128 * bj; xv[m][bj][0] = *(const f32x4*)xr; xv[m][bj][1] = *(const f32x4*)(xr + 4); }
; #pragma unroll
;                 for (int m = 0; m < 4; ++m) {
;                     float* orow = out + (size_t)(row0 + ai * 128 + m * 16) * DM;
; #pragma unroll
;                     for (int bj = 0; bj < 2; ++bj) {
;                         const int col = colb + 128 * bj;
;                         *(f32x4*)(orow + col) = acc[ai][bj][m][0] + xv[m][bj][0]; *(f32x4*)(orow + col + 4) = acc[ai][bj][m][1] + xv[m][bj][1];
;                     }
;                 }
;             }
.LBB0_809:
	v_readlane_b32 s18, v254, 30
	v_readlane_b32 s19, v254, 31
	v_bfe_u32 v150, v148, 3, 1
	v_and_b32_e32 v148, 0xfffffff7, v148
	v_lshl_add_u32 v142, v150, 2, v142
	v_lshlrev_b64 v[142:143], 2, v[142:143]
	v_lshlrev_b64 v[146:147], 13, v[148:149]
	v_lshl_add_u64 v[144:145], s[18:19], 0, v[142:143]
	v_lshl_add_u64 v[146:147], v[144:145], 0, v[146:147]
	s_mov_b32 s5, 0
	v_mov_b32_e32 v222, v124
	v_mov_b32_e32 v223, v125
	v_mov_b32_e32 v224, v126
	v_mov_b32_e32 v225, v127
	v_mov_b32_dpp v124, v120 row_ror:8 row_mask:0xf bank_mask:0xc
	v_mov_b32_dpp v125, v121 row_ror:8 row_mask:0xf bank_mask:0xc
	v_mov_b32_dpp v126, v122 row_ror:8 row_mask:0xf bank_mask:0xc
	v_mov_b32_dpp v127, v123 row_ror:8 row_mask:0xf bank_mask:0xc
	v_mov_b32_dpp v120, v222 row_ror:8 row_mask:0xf bank_mask:0x3
	v_mov_b32_dpp v121, v223 row_ror:8 row_mask:0xf bank_mask:0x3
	v_mov_b32_dpp v122, v224 row_ror:8 row_mask:0xf bank_mask:0x3
	v_mov_b32_dpp v123, v225 row_ror:8 row_mask:0xf bank_mask:0x3
	v_mov_b32_e32 v142, v116
	v_mov_b32_e32 v143, v117
	v_mov_b32_e32 v144, v118
	v_mov_b32_e32 v145, v119
	v_mov_b32_dpp v116, v112 row_ror:8 row_mask:0xf bank_mask:0xc
	v_mov_b32_dpp v117, v113 row_ror:8 row_mask:0xf bank_mask:0xc
	v_mov_b32_dpp v118, v114 row_ror:8 row_mask:0xf bank_mask:0xc
	v_mov_b32_dpp v119, v115 row_ror:8 row_mask:0xf bank_mask:0xc
	v_mov_b32_dpp v112, v142 row_ror:8 row_mask:0xf bank_mask:0x3
	v_mov_b32_dpp v113, v143 row_ror:8 row_mask:0xf bank_mask:0x3
	v_mov_b32_dpp v114, v144 row_ror:8 row_mask:0xf bank_mask:0x3
	v_mov_b32_dpp v115, v145 row_ror:8 row_mask:0xf bank_mask:0x3
	v_mov_b32_e32 v222, v108
	v_mov_b32_e32 v223, v109
	v_mov_b32_e32 v224, v110
	v_mov_b32_e32 v225, v111
	v_mov_b32_dpp v108, v104 row_ror:8 row_mask:0xf bank_mask:0xc
	v_mov_b32_dpp v109, v105 row_ror:8 row_mask:0xf bank_mask:0xc
	v_mov_b32_dpp v110, v106 row_ror:8 row_mask:0xf bank_mask:0xc
	v_mov_b32_dpp v111, v107 row_ror:8 row_mask:0xf bank_mask:0xc
	v_mov_b32_dpp v104, v222 row_ror:8 row_mask:0xf bank_mask:0x3
	v_mov_b32_dpp v105, v223 row_ror:8 row_mask:0xf bank_mask:0x3
	v_mov_b32_dpp v106, v224 row_ror:8 row_mask:0xf bank_mask:0x3
	v_mov_b32_dpp v107, v225 row_ror:8 row_mask:0xf bank_mask:0x3
	v_mov_b32_e32 v142, v100
	v_mov_b32_e32 v143, v101
	v_mov_b32_e32 v144, v102
	v_mov_b32_e32 v145, v103
	v_mov_b32_dpp v100, v96 row_ror:8 row_mask:0xf bank_mask:0xc
	v_mov_b32_dpp v101, v97 row_ror:8 row_mask:0xf bank_mask:0xc
	v_mov_b32_dpp v102, v98 row_ror:8 row_mask:0xf bank_mask:0xc
	v_mov_b32_dpp v103, v99 row_ror:8 row_mask:0xf bank_mask:0xc
	v_mov_b32_dpp v96, v142 row_ror:8 row_mask:0xf bank_mask:0x3
	v_mov_b32_dpp v97, v143 row_ror:8 row_mask:0xf bank_mask:0x3
	v_mov_b32_dpp v98, v144 row_ror:8 row_mask:0xf bank_mask:0x3
	v_mov_b32_dpp v99, v145 row_ror:8 row_mask:0xf bank_mask:0x3
	v_mov_b32_e32 v222, v92
	v_mov_b32_e32 v223, v93
	v_mov_b32_e32 v224, v94
	v_mov_b32_e32 v225, v95
	v_mov_b32_dpp v92, v88 row_ror:8 row_mask:0xf bank_mask:0xc
	v_mov_b32_dpp v93, v89 row_ror:8 row_mask:0xf bank_mask:0xc
	v_mov_b32_dpp v94, v90 row_ror:8 row_mask:0xf bank_mask:0xc
	v_mov_b32_dpp v95, v91 row_ror:8 row_mask:0xf bank_mask:0xc
	v_mov_b32_dpp v88, v222 row_ror:8 row_mask:0xf bank_mask:0x3
	v_mov_b32_dpp v89, v223 row_ror:8 row_mask:0xf bank_mask:0x3
	v_mov_b32_dpp v90, v224 row_ror:8 row_mask:0xf bank_mask:0x3
	v_mov_b32_dpp v91, v225 row_ror:8 row_mask:0xf bank_mask:0x3
	v_mov_b32_e32 v142, v84
	v_mov_b32_e32 v143, v85
	v_mov_b32_e32 v144, v86
	v_mov_b32_e32 v145, v87
	v_mov_b32_dpp v84, v80 row_ror:8 row_mask:0xf bank_mask:0xc
	v_mov_b32_dpp v85, v81 row_ror:8 row_mask:0xf bank_mask:0xc
	v_mov_b32_dpp v86, v82 row_ror:8 row_mask:0xf bank_mask:0xc
	v_mov_b32_dpp v87, v83 row_ror:8 row_mask:0xf bank_mask:0xc
	v_mov_b32_dpp v80, v142 row_ror:8 row_mask:0xf bank_mask:0x3
	v_mov_b32_dpp v81, v143 row_ror:8 row_mask:0xf bank_mask:0x3
	v_mov_b32_dpp v82, v144 row_ror:8 row_mask:0xf bank_mask:0x3
	v_mov_b32_dpp v83, v145 row_ror:8 row_mask:0xf bank_mask:0x3
	v_mov_b32_e32 v222, v76
	v_mov_b32_e32 v223, v77
	v_mov_b32_e32 v224, v78
	v_mov_b32_e32 v225, v79
	v_mov_b32_dpp v76, v72 row_ror:8 row_mask:0xf bank_mask:0xc
	v_mov_b32_dpp v77, v73 row_ror:8 row_mask:0xf bank_mask:0xc
	v_mov_b32_dpp v78, v74 row_ror:8 row_mask:0xf bank_mask:0xc
	v_mov_b32_dpp v79, v75 row_ror:8 row_mask:0xf bank_mask:0xc
	v_mov_b32_dpp v72, v222 row_ror:8 row_mask:0xf bank_mask:0x3
	v_mov_b32_dpp v73, v223 row_ror:8 row_mask:0xf bank_mask:0x3
	v_mov_b32_dpp v74, v224 row_ror:8 row_mask:0xf bank_mask:0x3
	v_mov_b32_dpp v75, v225 row_ror:8 row_mask:0xf bank_mask:0x3
	v_mov_b32_e32 v142, v68
	v_mov_b32_e32 v143, v69
	v_mov_b32_e32 v144, v70
	v_mov_b32_e32 v145, v71
	v_mov_b32_dpp v68, v64 row_ror:8 row_mask:0xf bank_mask:0xc
	v_mov_b32_dpp v69, v65 row_ror:8 row_mask:0xf bank_mask:0xc
	v_mov_b32_dpp v70, v66 row_ror:8 row_mask:0xf bank_mask:0xc
	v_mov_b32_dpp v71, v67 row_ror:8 row_mask:0xf bank_mask:0xc
	v_mov_b32_dpp v64, v142 row_ror:8 row_mask:0xf bank_mask:0x3
	v_mov_b32_dpp v65, v143 row_ror:8 row_mask:0xf bank_mask:0x3
	v_mov_b32_dpp v66, v144 row_ror:8 row_mask:0xf bank_mask:0x3
	v_mov_b32_dpp v67, v145 row_ror:8 row_mask:0xf bank_mask:0x3
	v_mov_b32_e32 v222, v60
	v_mov_b32_e32 v223, v61
	v_mov_b32_e32 v224, v62
	v_mov_b32_e32 v225, v63
	v_mov_b32_dpp v60, v56 row_ror:8 row_mask:0xf bank_mask:0xc
	v_mov_b32_dpp v61, v57 row_ror:8 row_mask:0xf bank_mask:0xc
	v_mov_b32_dpp v62, v58 row_ror:8 row_mask:0xf bank_mask:0xc
	v_mov_b32_dpp v63, v59 row_ror:8 row_mask:0xf bank_mask:0xc
	v_mov_b32_dpp v56, v222 row_ror:8 row_mask:0xf bank_mask:0x3
	v_mov_b32_dpp v57, v223 row_ror:8 row_mask:0xf bank_mask:0x3
;     __device__ __forceinline__ void operator()(const f32x4 (&acc)[2][2][4][2], const pg8::Unit& u, int wr, int wc, int fr, int fq) const {
;         const int row0 = u.pm * 256 + wr * 64 + fr; const int colb = u.pn * 256 + 32 * wc + 8 * fq;
;         if (u.nt == 0) {
; #pragma unroll
;             for (int ai = 0; ai < 2; ++ai) {
;                 f32x4 xv[4][2][2];
; #pragma unroll
;                 for (int m = 0; m < 4; ++m)
; #pragma unroll
;                     for (int bj = 0; bj < 2; ++bj) { const float* xr = out + (size_t)(row0 + ai * 128 + m * 16) * DM + colb + 128 * bj; xv[m][bj][0] = *(const f32x4*)xr; xv[m][bj][1] = *(const f32x4*)(xr + 4); }
; #pragma unroll
;                 for (int m = 0; m < 4; ++m) {
;                     float* orow = out + (size_t)(row0 + ai * 128 + m * 16) * DM;
; #pragma unroll
;                     for (int bj = 0; bj < 2; ++bj) {
;                         const int col = colb + 128 * bj;
;                         *(f32x4*)(orow + col) = acc[ai][bj][m][0] + xv[m][bj][0]; *(f32x4*)(orow + col + 4) = acc[ai][bj][m][1] + xv[m][bj][1];
;                     }
;                 }
;             }
	v_mov_b32_dpp v58, v224 row_ror:8 row_mask:0xf bank_mask:0x3
	v_mov_b32_dpp v59, v225 row_ror:8 row_mask:0xf bank_mask:0x3
	v_mov_b32_e32 v142, v52
	v_mov_b32_e32 v143, v53
	v_mov_b32_e32 v144, v54
	v_mov_b32_e32 v145, v55
	v_mov_b32_dpp v52, v48 row_ror:8 row_mask:0xf bank_mask:0xc
	v_mov_b32_dpp v53, v49 row_ror:8 row_mask:0xf bank_mask:0xc
	v_mov_b32_dpp v54, v50 row_ror:8 row_mask:0xf bank_mask:0xc
	v_mov_b32_dpp v55, v51 row_ror:8 row_mask:0xf bank_mask:0xc
	v_mov_b32_dpp v48, v142 row_ror:8 row_mask:0xf bank_mask:0x3
	v_mov_b32_dpp v49, v143 row_ror:8 row_mask:0xf bank_mask:0x3
	v_mov_b32_dpp v50, v144 row_ror:8 row_mask:0xf bank_mask:0x3
	v_mov_b32_dpp v51, v145 row_ror:8 row_mask:0xf bank_mask:0x3
	v_mov_b32_e32 v222, v44
	v_mov_b32_e32 v223, v45
	v_mov_b32_e32 v224, v46
	v_mov_b32_e32 v225, v47
	v_mov_b32_dpp v44, v40 row_ror:8 row_mask:0xf bank_mask:0xc
	v_mov_b32_dpp v45, v41 row_ror:8 row_mask:0xf bank_mask:0xc
	v_mov_b32_dpp v46, v42 row_ror:8 row_mask:0xf bank_mask:0xc
	v_mov_b32_dpp v47, v43 row_ror:8 row_mask:0xf bank_mask:0xc
	v_mov_b32_dpp v40, v222 row_ror:8 row_mask:0xf bank_mask:0x3
	v_mov_b32_dpp v41, v223 row_ror:8 row_mask:0xf bank_mask:0x3
	v_mov_b32_dpp v42, v224 row_ror:8 row_mask:0xf bank_mask:0x3
	v_mov_b32_dpp v43, v225 row_ror:8 row_mask:0xf bank_mask:0x3
	v_mov_b32_e32 v142, v36
	v_mov_b32_e32 v143, v37
	v_mov_b32_e32 v144, v38
	v_mov_b32_e32 v145, v39
	v_mov_b32_dpp v36, v32 row_ror:8 row_mask:0xf bank_mask:0xc
	v_mov_b32_dpp v37, v33 row_ror:8 row_mask:0xf bank_mask:0xc
	v_mov_b32_dpp v38, v34 row_ror:8 row_mask:0xf bank_mask:0xc
	v_mov_b32_dpp v39, v35 row_ror:8 row_mask:0xf bank_mask:0xc
	v_mov_b32_dpp v32, v142 row_ror:8 row_mask:0xf bank_mask:0x3
	v_mov_b32_dpp v33, v143 row_ror:8 row_mask:0xf bank_mask:0x3
	v_mov_b32_dpp v34, v144 row_ror:8 row_mask:0xf bank_mask:0x3
	v_mov_b32_dpp v35, v145 row_ror:8 row_mask:0xf bank_mask:0x3
	v_mov_b32_e32 v222, v28
	v_mov_b32_e32 v223, v29
	v_mov_b32_e32 v224, v30
	v_mov_b32_e32 v225, v31
	v_mov_b32_dpp v28, v24 row_ror:8 row_mask:0xf bank_mask:0xc
	v_mov_b32_dpp v29, v25 row_ror:8 row_mask:0xf bank_mask:0xc
	v_mov_b32_dpp v30, v26 row_ror:8 row_mask:0xf bank_mask:0xc
	v_mov_b32_dpp v31, v27 row_ror:8 row_mask:0xf bank_mask:0xc
	v_mov_b32_dpp v24, v222 row_ror:8 row_mask:0xf bank_mask:0x3
	v_mov_b32_dpp v25, v223 row_ror:8 row_mask:0xf bank_mask:0x3
	v_mov_b32_dpp v26, v224 row_ror:8 row_mask:0xf bank_mask:0x3
	v_mov_b32_dpp v27, v225 row_ror:8 row_mask:0xf bank_mask:0x3
	v_mov_b32_e32 v142, v20
	v_mov_b32_e32 v143, v21
	v_mov_b32_e32 v144, v22
	v_mov_b32_e32 v145, v23
	v_mov_b32_dpp v20, v16 row_ror:8 row_mask:0xf bank_mask:0xc
	v_mov_b32_dpp v21, v17 row_ror:8 row_mask:0xf bank_mask:0xc
	v_mov_b32_dpp v22, v18 row_ror:8 row_mask:0xf bank_mask:0xc
	v_mov_b32_dpp v23, v19 row_ror:8 row_mask:0xf bank_mask:0xc
	v_mov_b32_dpp v16, v142 row_ror:8 row_mask:0xf bank_mask:0x3
	v_mov_b32_dpp v17, v143 row_ror:8 row_mask:0xf bank_mask:0x3
	v_mov_b32_dpp v18, v144 row_ror:8 row_mask:0xf bank_mask:0x3
	v_mov_b32_dpp v19, v145 row_ror:8 row_mask:0xf bank_mask:0x3
	v_mov_b32_e32 v222, v12
	v_mov_b32_e32 v223, v13
	v_mov_b32_e32 v224, v14
	v_mov_b32_e32 v225, v15
	v_mov_b32_dpp v12, v8 row_ror:8 row_mask:0xf bank_mask:0xc
	v_mov_b32_dpp v13, v9 row_ror:8 row_mask:0xf bank_mask:0xc
	v_mov_b32_dpp v14, v10 row_ror:8 row_mask:0xf bank_mask:0xc
	v_mov_b32_dpp v15, v11 row_ror:8 row_mask:0xf bank_mask:0xc
	v_mov_b32_dpp v8, v222 row_ror:8 row_mask:0xf bank_mask:0x3
	v_mov_b32_dpp v9, v223 row_ror:8 row_mask:0xf bank_mask:0x3
	v_mov_b32_dpp v10, v224 row_ror:8 row_mask:0xf bank_mask:0x3
	v_mov_b32_dpp v11, v225 row_ror:8 row_mask:0xf bank_mask:0x3
	v_mov_b32_e32 v142, v4
	v_mov_b32_e32 v143, v5
	v_mov_b32_e32 v144, v6
	v_mov_b32_e32 v145, v7
	v_mov_b32_dpp v4, v0 row_ror:8 row_mask:0xf bank_mask:0xc
	v_mov_b32_dpp v5, v1 row_ror:8 row_mask:0xf bank_mask:0xc
	v_mov_b32_dpp v6, v2 row_ror:8 row_mask:0xf bank_mask:0xc
	v_mov_b32_dpp v7, v3 row_ror:8 row_mask:0xf bank_mask:0xc
	v_mov_b32_dpp v0, v142 row_ror:8 row_mask:0xf bank_mask:0x3
	v_mov_b32_dpp v1, v143 row_ror:8 row_mask:0xf bank_mask:0x3
	v_mov_b32_dpp v2, v144 row_ror:8 row_mask:0xf bank_mask:0x3
	v_mov_b32_dpp v3, v145 row_ror:8 row_mask:0xf bank_mask:0x3
	s_mov_b32 s4, 0x0
	v_lshl_add_u64 v[224:225], v[146:147], 0, s[4:5]
	global_load_dwordx4 v[160:163], v[224:225], off
	global_load_dwordx4 v[168:171], v[224:225], off offset:512
	s_mov_b32 s4, 0x10000
	v_lshl_add_u64 v[226:227], v[146:147], 0, s[4:5]
	global_load_dwordx4 v[164:167], v[226:227], off
	global_load_dwordx4 v[172:175], v[226:227], off offset:512
	s_mov_b32 s4, 0x20000
	v_lshl_add_u64 v[224:225], v[146:147], 0, s[4:5]
	global_load_dwordx4 v[176:179], v[224:225], off
	global_load_dwordx4 v[184:187], v[224:225], off offset:512
	s_mov_b32 s4, 0x30000
	v_lshl_add_u64 v[226:227], v[146:147], 0, s[4:5]
	global_load_dwordx4 v[180:183], v[226:227], off
	global_load_dwordx4 v[190:193], v[226:227], off offset:512
	s_mov_b32 s4, 0x40000
	v_lshl_add_u64 v[224:225], v[146:147], 0, s[4:5]
	global_load_dwordx4 v[194:197], v[224:225], off
	global_load_dwordx4 v[202:205], v[224:225], off offset:512
	s_mov_b32 s4, 0x50000
	v_lshl_add_u64 v[226:227], v[146:147], 0, s[4:5]
	global_load_dwordx4 v[198:201], v[226:227], off
	global_load_dwordx4 v[206:209], v[226:227], off offset:512
	s_mov_b32 s4, 0x60000
	v_lshl_add_u64 v[224:225], v[146:147], 0, s[4:5]
	global_load_dwordx4 v[210:213], v[224:225], off
	global_load_dwordx4 v[218:221], v[224:225], off offset:512
	s_mov_b32 s4, 0x70000
	v_lshl_add_u64 v[226:227], v[146:147], 0, s[4:5]
	global_load_dwordx4 v[214:217], v[226:227], off
	global_load_dwordx4 v[150:153], v[226:227], off offset:512
	s_waitcnt vmcnt(0)
;     __device__ __forceinline__ void operator()(const f32x4 (&acc)[2][2][4][2], const pg8::Unit& u, int wr, int wc, int fr, int fq) const {
;         const int row0 = u.pm * 256 + wr * 64 + fr; const int colb = u.pn * 256 + 32 * wc + 8 * fq;
;         if (u.nt == 0) {
; #pragma unroll
;             for (int ai = 0; ai < 2; ++ai) {
;                 f32x4 xv[4][2][2];
; #pragma unroll
;                 for (int m = 0; m < 4; ++m)
; #pragma unroll
;                     for (int bj = 0; bj < 2; ++bj) { const float* xr = out + (size_t)(row0 + ai * 128 + m * 16) * DM + colb + 128 * bj; xv[m][bj][0] = *(const f32x4*)xr; xv[m][bj][1] = *(const f32x4*)(xr + 4); }
; #pragma unroll
;                 for (int m = 0; m < 4; ++m) {
;                     float* orow = out + (size_t)(row0 + ai * 128 + m * 16) * DM;
; #pragma unroll
;                     for (int bj = 0; bj < 2; ++bj) {
;                         const int col = colb + 128 * bj;
;                         *(f32x4*)(orow + col) = acc[ai][bj][m][0] + xv[m][bj][0]; *(f32x4*)(orow + col + 4) = acc[ai][bj][m][1] + xv[m][bj][1];
;                     }
;                 }
;             }
	v_pk_add_f32 v[124:125], v[124:125], v[160:161]
	v_pk_add_f32 v[126:127], v[126:127], v[162:163]
	v_pk_add_f32 v[120:121], v[120:121], v[164:165]
	v_pk_add_f32 v[122:123], v[122:123], v[166:167]
	v_pk_add_f32 v[116:117], v[116:117], v[168:169]
	v_pk_add_f32 v[118:119], v[118:119], v[170:171]
	v_pk_add_f32 v[112:113], v[112:113], v[172:173]
	v_pk_add_f32 v[114:115], v[114:115], v[174:175]
	v_pk_add_f32 v[108:109], v[108:109], v[176:177]
	v_pk_add_f32 v[110:111], v[110:111], v[178:179]
	v_pk_add_f32 v[104:105], v[104:105], v[180:181]
	v_pk_add_f32 v[106:107], v[106:107], v[182:183]
	v_pk_add_f32 v[100:101], v[100:101], v[184:185]
	v_pk_add_f32 v[102:103], v[102:103], v[186:187]
	v_pk_add_f32 v[96:97], v[96:97], v[190:191]
	v_pk_add_f32 v[98:99], v[98:99], v[192:193]
	v_pk_add_f32 v[92:93], v[92:93], v[194:195]
	v_pk_add_f32 v[94:95], v[94:95], v[196:197]
	v_pk_add_f32 v[88:89], v[88:89], v[198:199]
	v_pk_add_f32 v[90:91], v[90:91], v[200:201]
	v_pk_add_f32 v[84:85], v[84:85], v[202:203]
	v_pk_add_f32 v[86:87], v[86:87], v[204:205]
	v_pk_add_f32 v[80:81], v[80:81], v[206:207]
	v_pk_add_f32 v[82:83], v[82:83], v[208:209]
	v_pk_add_f32 v[76:77], v[76:77], v[210:211]
	v_pk_add_f32 v[78:79], v[78:79], v[212:213]
	v_pk_add_f32 v[72:73], v[72:73], v[214:215]
	v_pk_add_f32 v[74:75], v[74:75], v[216:217]
	v_pk_add_f32 v[68:69], v[68:69], v[218:219]
	v_pk_add_f32 v[70:71], v[70:71], v[220:221]
	v_pk_add_f32 v[64:65], v[64:65], v[150:151]
	v_pk_add_f32 v[66:67], v[66:67], v[152:153]
	s_mov_b32 s4, 0x0
	v_lshl_add_u64 v[224:225], v[146:147], 0, s[4:5]
	global_store_dwordx4 v[224:225], v[124:127], off
	global_store_dwordx4 v[224:225], v[116:119], off offset:512
	s_mov_b32 s4, 0x10000
	v_lshl_add_u64 v[226:227], v[146:147], 0, s[4:5]
	global_store_dwordx4 v[226:227], v[120:123], off
	global_store_dwordx4 v[226:227], v[112:115], off offset:512
	s_mov_b32 s4, 0x20000
	v_lshl_add_u64 v[224:225], v[146:147], 0, s[4:5]
	global_store_dwordx4 v[224:225], v[108:111], off
	global_store_dwordx4 v[224:225], v[100:103], off offset:512
	s_mov_b32 s4, 0x30000
	v_lshl_add_u64 v[226:227], v[146:147], 0, s[4:5]
	global_store_dwordx4 v[226:227], v[104:107], off
	global_store_dwordx4 v[226:227], v[96:99], off offset:512
	s_mov_b32 s4, 0x40000
	v_lshl_add_u64 v[224:225], v[146:147], 0, s[4:5]
	global_store_dwordx4 v[224:225], v[92:95], off
	global_store_dwordx4 v[224:225], v[84:87], off offset:512
	s_mov_b32 s4, 0x50000
	v_lshl_add_u64 v[226:227], v[146:147], 0, s[4:5]
	global_store_dwordx4 v[226:227], v[88:91], off
	global_store_dwordx4 v[226:227], v[80:83], off offset:512
	s_mov_b32 s4, 0x60000
	v_lshl_add_u64 v[224:225], v[146:147], 0, s[4:5]
	global_store_dwordx4 v[224:225], v[76:79], off
	global_store_dwordx4 v[224:225], v[68:71], off offset:512
	s_mov_b32 s4, 0x70000
	v_lshl_add_u64 v[226:227], v[146:147], 0, s[4:5]
	global_store_dwordx4 v[226:227], v[72:75], off
	global_store_dwordx4 v[226:227], v[64:67], off offset:512
	s_mov_b32 s4, 0x100000
	v_lshl_add_u64 v[224:225], v[146:147], 0, s[4:5]
	global_load_dwordx4 v[160:163], v[224:225], off
	global_load_dwordx4 v[168:171], v[224:225], off offset:512
	s_mov_b32 s4, 0x110000
	v_lshl_add_u64 v[226:227], v[146:147], 0, s[4:5]
	global_load_dwordx4 v[164:167], v[226:227], off
	global_load_dwordx4 v[172:175], v[226:227], off offset:512
	s_mov_b32 s4, 0x120000
	v_lshl_add_u64 v[224:225], v[146:147], 0, s[4:5]
	global_load_dwordx4 v[176:179], v[224:225], off
	global_load_dwordx4 v[184:187], v[224:225], off offset:512
	s_mov_b32 s4, 0x130000
	v_lshl_add_u64 v[226:227], v[146:147], 0, s[4:5]
	global_load_dwordx4 v[180:183], v[226:227], off
	global_load_dwordx4 v[190:193], v[226:227], off offset:512
	s_mov_b32 s4, 0x140000
	v_lshl_add_u64 v[224:225], v[146:147], 0, s[4:5]
	global_load_dwordx4 v[194:197], v[224:225], off
	global_load_dwordx4 v[202:205], v[224:225], off offset:512
	s_mov_b32 s4, 0x150000
	v_lshl_add_u64 v[226:227], v[146:147], 0, s[4:5]
	global_load_dwordx4 v[198:201], v[226:227], off
	global_load_dwordx4 v[206:209], v[226:227], off offset:512
	s_mov_b32 s4, 0x160000
	v_lshl_add_u64 v[224:225], v[146:147], 0, s[4:5]
	global_load_dwordx4 v[210:213], v[224:225], off
	global_load_dwordx4 v[218:221], v[224:225], off offset:512
	s_mov_b32 s4, 0x170000
	v_lshl_add_u64 v[226:227], v[146:147], 0, s[4:5]
	global_load_dwordx4 v[214:217], v[226:227], off
	global_load_dwordx4 v[150:153], v[226:227], off offset:512
	s_waitcnt vmcnt(0)
;     __device__ __forceinline__ void operator()(const f32x4 (&acc)[2][2][4][2], const pg8::Unit& u, int wr, int wc, int fr, int fq) const {
;         const int row0 = u.pm * 256 + wr * 64 + fr; const int colb = u.pn * 256 + 32 * wc + 8 * fq;
;         if (u.nt == 0) {
; #pragma unroll
;             for (int ai = 0; ai < 2; ++ai) {
;                 f32x4 xv[4][2][2];
; #pragma unroll
;                 for (int m = 0; m < 4; ++m)
; #pragma unroll
;                     for (int bj = 0; bj < 2; ++bj) { const float* xr = out + (size_t)(row0 + ai * 128 + m * 16) * DM + colb + 128 * bj; xv[m][bj][0] = *(const f32x4*)xr; xv[m][bj][1] = *(const f32x4*)(xr + 4); }
; #pragma unroll
;                 for (int m = 0; m < 4; ++m) {
;                     float* orow = out + (size_t)(row0 + ai * 128 + m * 16) * DM;
; #pragma unroll
;                     for (int bj = 0; bj < 2; ++bj) {
;                         const int col = colb + 128 * bj;
;                         *(f32x4*)(orow + col) = acc[ai][bj][m][0] + xv[m][bj][0]; *(f32x4*)(orow + col + 4) = acc[ai][bj][m][1] + xv[m][bj][1];
;                     }
;                 }
;             }
	v_pk_add_f32 v[60:61], v[60:61], v[160:161]
	v_pk_add_f32 v[62:63], v[62:63], v[162:163]
	v_pk_add_f32 v[56:57], v[56:57], v[164:165]
	v_pk_add_f32 v[58:59], v[58:59], v[166:167]
	v_pk_add_f32 v[52:53], v[52:53], v[168:169]
	v_pk_add_f32 v[54:55], v[54:55], v[170:171]
	v_pk_add_f32 v[48:49], v[48:49], v[172:173]
	v_pk_add_f32 v[50:51], v[50:51], v[174:175]
	v_pk_add_f32 v[44:45], v[44:45], v[176:177]
	v_pk_add_f32 v[46:47], v[46:47], v[178:179]
	v_pk_add_f32 v[40:41], v[40:41], v[180:181]
	v_pk_add_f32 v[42:43], v[42:43], v[182:183]
	v_pk_add_f32 v[36:37], v[36:37], v[184:185]
	v_pk_add_f32 v[38:39], v[38:39], v[186:187]
	v_pk_add_f32 v[32:33], v[32:33], v[190:191]
	v_pk_add_f32 v[34:35], v[34:35], v[192:193]
	v_pk_add_f32 v[28:29], v[28:29], v[194:195]
	v_pk_add_f32 v[30:31], v[30:31], v[196:197]
	v_pk_add_f32 v[24:25], v[24:25], v[198:199]
	v_pk_add_f32 v[26:27], v[26:27], v[200:201]
	v_pk_add_f32 v[20:21], v[20:21], v[202:203]
	v_pk_add_f32 v[22:23], v[22:23], v[204:205]
	v_pk_add_f32 v[16:17], v[16:17], v[206:207]
	v_pk_add_f32 v[18:19], v[18:19], v[208:209]
	v_pk_add_f32 v[12:13], v[12:13], v[210:211]
	v_pk_add_f32 v[14:15], v[14:15], v[212:213]
	v_pk_add_f32 v[8:9], v[8:9], v[214:215]
	v_pk_add_f32 v[10:11], v[10:11], v[216:217]
	v_pk_add_f32 v[4:5], v[4:5], v[218:219]
	v_pk_add_f32 v[6:7], v[6:7], v[220:221]
	v_pk_add_f32 v[0:1], v[0:1], v[150:151]
	v_pk_add_f32 v[2:3], v[2:3], v[152:153]
	s_mov_b32 s4, 0x100000
	v_lshl_add_u64 v[224:225], v[146:147], 0, s[4:5]
	global_store_dwordx4 v[224:225], v[60:63], off
	global_store_dwordx4 v[224:225], v[52:55], off offset:512
	s_mov_b32 s4, 0x110000
	v_lshl_add_u64 v[226:227], v[146:147], 0, s[4:5]
	global_store_dwordx4 v[226:227], v[56:59], off
	global_store_dwordx4 v[226:227], v[48:51], off offset:512
	s_mov_b32 s4, 0x120000
	v_lshl_add_u64 v[224:225], v[146:147], 0, s[4:5]
	global_store_dwordx4 v[224:225], v[44:47], off
	global_store_dwordx4 v[224:225], v[36:39], off offset:512
	s_mov_b32 s4, 0x130000
	v_lshl_add_u64 v[226:227], v[146:147], 0, s[4:5]
	global_store_dwordx4 v[226:227], v[40:43], off
	global_store_dwordx4 v[226:227], v[32:35], off offset:512
	s_mov_b32 s4, 0x140000
	v_lshl_add_u64 v[224:225], v[146:147], 0, s[4:5]
	global_store_dwordx4 v[224:225], v[28:31], off
	global_store_dwordx4 v[224:225], v[20:23], off offset:512
	s_mov_b32 s4, 0x150000
	v_lshl_add_u64 v[226:227], v[146:147], 0, s[4:5]
	global_store_dwordx4 v[226:227], v[24:27], off
	global_store_dwordx4 v[226:227], v[16:19], off offset:512
	s_mov_b32 s4, 0x160000
	v_lshl_add_u64 v[224:225], v[146:147], 0, s[4:5]
	global_store_dwordx4 v[224:225], v[12:15], off
	global_store_dwordx4 v[224:225], v[4:7], off offset:512
	s_mov_b32 s4, 0x170000
	v_lshl_add_u64 v[226:227], v[146:147], 0, s[4:5]
	global_store_dwordx4 v[226:227], v[8:11], off
	global_store_dwordx4 v[226:227], v[0:3], off offset:512
	v_readlane_b32 s4, v254, 16
	v_readlane_b32 s5, v254, 17
	v_readlane_b32 s6, v254, 18
	v_readlane_b32 s7, v254, 19
	v_readlane_b32 s8, v254, 20
	v_readlane_b32 s9, v254, 21
	v_readlane_b32 s10, v254, 22
	v_readlane_b32 s11, v254, 23
	v_readlane_b32 s12, v254, 24
	v_readlane_b32 s13, v254, 25
	v_readlane_b32 s14, v254, 26
	v_readlane_b32 s15, v254, 27
	v_readlane_b32 s16, v254, 28
	v_readlane_b32 s17, v254, 29
	s_and_b64 vcc, exec, s[2:3]
	s_mov_b64 s[2:3], -1
	s_cbranch_vccnz .LBB0_784
